# stack: K-loop edges + GLA prologue hoists + LDS-read software pipelining in GLA step A/C and the attention merge
# speedup vs baseline: 1.0003x; 1.0003x over previous
; __device__ __forceinline__ unsigned pk2(float lo, float hi) { return pg8::cvt_pk_bf16(lo, hi); }
;     ...
;     if (kh == 0) {
; #pragma unroll
;         for (int rb = 0; rb < 2; ++rb) {
;             float l = lrun[rb] + X[(rp * 68 + 66 + rb) * 64 + lane]; l += __shfl_xor(l, 16); l += __shfl_xor(l, 32);
;             const float inv = 1.0f / l;
;             bf16* orow = Op + (size_t)(32 * rp + 16 * rb + fr) * ldo + 4 * fq;
; #pragma unroll
;             for (int db = 0; db < 8; ++db) { float v[4];
; #pragma unroll
;                 for (int i = 0; i < 4; ++i) v[i] = (o[rb][db][i] + X[(rp * 68 + rb * 32 + db * 4 + i) * 64 + lane]) * inv;
;                 u32x2 ov; ov.x = pk2(v[0], v[1]); ov.y = pk2(v[2], v[3]); *(u32x2*)(orow + 16 * db) = ov; }
.LBB0_130:
	s_or_b64 exec, exec, s[78:79]
	s_waitcnt lgkmcnt(0)
	s_barrier
	s_and_saveexec_b64 s[40:41], vcc
	s_cbranch_execz .LBB0_115
	v_lshrrev_b32_e32 v33, 1, v155
	v_and_b32_e32 v152, 24, v33
	ds_read_b32 v33, v38 offset:16896
	s_lshl_b64 s[58:59], s[76:77], 12
	s_add_u32 s58, s54, s58
	s_addc_u32 s59, s55, s59
	v_lshl_add_u64 v[34:35], s[58:59], 0, v[152:153]
	s_waitcnt lgkmcnt(0)
	v_add_f32_e32 v33, v151, v33
	ds_bpermute_b32 v36, v162, v33
	v_ashrrev_i32_e32 v157, 31, v156
	v_or_b32_e32 v32, 16, v156
	s_waitcnt lgkmcnt(0)
	v_add_f32_e32 v33, v33, v36
	ds_bpermute_b32 v36, v163, v33
	s_waitcnt lgkmcnt(0)
	v_add_f32_e32 v33, v33, v36
	v_div_scale_f32 v36, s[58:59], v33, v33, 1.0
	v_rcp_f32_e32 v37, v36
	s_nop 0
	v_fma_f32 v39, -v36, v37, 1.0
	v_fmac_f32_e32 v37, v39, v37
	v_div_scale_f32 v39, vcc, 1.0, v33, 1.0
	s_waitcnt vmcnt(1)
	v_mul_f32_e32 v40, v39, v37
	v_fma_f32 v41, -v36, v40, v39
	v_fmac_f32_e32 v40, v41, v37
	v_fma_f32 v36, -v36, v40, v39
	v_div_fmas_f32 v36, v36, v37, v40
	ds_read2st64_b32 v[228:229], v38 offset1:1
	ds_read2st64_b32 v[232:233], v38 offset0:2 offset1:3
	ds_read2st64_b32 v[240:241], v38 offset0:4 offset1:5
	ds_read2st64_b32 v[244:245], v38 offset0:6 offset1:7
	ds_read2st64_b32 v[248:249], v38 offset0:8 offset1:9
	v_div_fixup_f32 v33, v36, v33, 1.0
	v_lshlrev_b64 v[36:37], 12, v[156:157]
	v_lshl_add_u64 v[36:37], v[34:35], 0, v[36:37]
	s_waitcnt lgkmcnt(4)
	v_add_f32_e32 v39, v124, v228
	v_add_f32_e32 v40, v125, v229
	ds_read2st64_b32 v[228:229], v38 offset0:10 offset1:11
	v_mul_f32_e32 v42, v33, v40
	v_mul_f32_e32 v39, v39, v33
	s_waitcnt lgkmcnt(4)
	v_add_f32_e32 v40, v126, v232
	v_mul_f32_e32 v43, v33, v40
	v_add_f32_e32 v40, v127, v233
	ds_read2st64_b32 v[232:233], v38 offset0:12 offset1:13
	v_mul_f32_e32 v41, v33, v40
	v_cvt_pk_bf16_f32 v40, v39, v42
	v_cvt_pk_bf16_f32 v41, v43, v41
	global_store_dwordx2 v[36:37], v[40:41], off
	s_waitcnt lgkmcnt(4)
	v_add_f32_e32 v39, v120, v240
	v_add_f32_e32 v40, v121, v241
	ds_read2st64_b32 v[240:241], v38 offset0:14 offset1:15
	v_mul_f32_e32 v42, v33, v40
	v_mul_f32_e32 v39, v33, v39
	s_waitcnt lgkmcnt(4)
	v_add_f32_e32 v40, v122, v244
	v_mul_f32_e32 v43, v33, v40
	v_add_f32_e32 v40, v123, v245
	ds_read2st64_b32 v[244:245], v38 offset0:16 offset1:17
	v_mul_f32_e32 v41, v33, v40
	v_cvt_pk_bf16_f32 v40, v39, v42
	v_cvt_pk_bf16_f32 v41, v43, v41
	global_store_dwordx2 v[36:37], v[40:41], off offset:32
	s_waitcnt lgkmcnt(4)
	v_add_f32_e32 v39, v116, v248
	v_add_f32_e32 v40, v117, v249
	ds_read2st64_b32 v[248:249], v38 offset0:18 offset1:19
	v_mul_f32_e32 v42, v33, v40
	v_mul_f32_e32 v39, v33, v39
	s_waitcnt lgkmcnt(4)
	v_add_f32_e32 v40, v118, v228
	v_mul_f32_e32 v43, v33, v40
	v_add_f32_e32 v40, v119, v229
	ds_read2st64_b32 v[228:229], v38 offset0:20 offset1:21
	v_mul_f32_e32 v41, v33, v40
	v_cvt_pk_bf16_f32 v40, v39, v42
	v_cvt_pk_bf16_f32 v41, v43, v41
	global_store_dwordx2 v[36:37], v[40:41], off offset:64
	s_waitcnt lgkmcnt(4)
	v_add_f32_e32 v39, v112, v232
	v_add_f32_e32 v40, v113, v233
	ds_read2st64_b32 v[232:233], v38 offset0:22 offset1:23
	v_mul_f32_e32 v42, v33, v40
	v_mul_f32_e32 v39, v33, v39
	s_waitcnt lgkmcnt(4)
	v_add_f32_e32 v40, v114, v240
	v_mul_f32_e32 v43, v33, v40
	v_add_f32_e32 v40, v115, v241
	ds_read2st64_b32 v[240:241], v38 offset0:24 offset1:25
	v_mul_f32_e32 v41, v33, v40
	v_cvt_pk_bf16_f32 v40, v39, v42
	v_cvt_pk_bf16_f32 v41, v43, v41
	global_store_dwordx2 v[36:37], v[40:41], off offset:96
	s_waitcnt lgkmcnt(4)
	v_add_f32_e32 v39, v108, v244
	v_add_f32_e32 v40, v109, v245
	ds_read2st64_b32 v[244:245], v38 offset0:26 offset1:27
	v_mul_f32_e32 v42, v33, v40
	v_mul_f32_e32 v39, v33, v39
	s_waitcnt lgkmcnt(4)
	v_add_f32_e32 v40, v110, v248
	v_mul_f32_e32 v43, v33, v40
	v_add_f32_e32 v40, v111, v249
	ds_read2st64_b32 v[248:249], v38 offset0:28 offset1:29
	v_mul_f32_e32 v41, v33, v40
	v_cvt_pk_bf16_f32 v40, v39, v42
	v_cvt_pk_bf16_f32 v41, v43, v41
	global_store_dwordx2 v[36:37], v[40:41], off offset:128
	s_waitcnt lgkmcnt(4)
	v_add_f32_e32 v39, v72, v228
	v_add_f32_e32 v40, v73, v229
	ds_read2st64_b32 v[228:229], v38 offset0:30 offset1:31
	v_mul_f32_e32 v42, v33, v40
	v_mul_f32_e32 v39, v33, v39
	s_waitcnt lgkmcnt(4)
	v_add_f32_e32 v40, v74, v232
	v_mul_f32_e32 v43, v33, v40
	v_add_f32_e32 v40, v75, v233
	v_mul_f32_e32 v41, v33, v40
	v_cvt_pk_bf16_f32 v40, v39, v42
	v_cvt_pk_bf16_f32 v41, v43, v41
	global_store_dwordx2 v[36:37], v[40:41], off offset:160
	s_waitcnt lgkmcnt(3)
	v_add_f32_e32 v39, v68, v240
	v_add_f32_e32 v40, v69, v241
	v_mul_f32_e32 v42, v33, v40
	v_mul_f32_e32 v39, v33, v39
	s_waitcnt lgkmcnt(2)
	v_add_f32_e32 v40, v70, v244
	v_mul_f32_e32 v43, v33, v40
	v_add_f32_e32 v40, v71, v245
	v_mul_f32_e32 v41, v33, v40
	v_cvt_pk_bf16_f32 v40, v39, v42
	v_cvt_pk_bf16_f32 v41, v43, v41
	global_store_dwordx2 v[36:37], v[40:41], off offset:192
	s_waitcnt lgkmcnt(1)
	v_add_f32_e32 v39, v64, v248
	v_add_f32_e32 v40, v65, v249
	v_mul_f32_e32 v42, v33, v40
	v_mul_f32_e32 v39, v33, v39
	s_waitcnt lgkmcnt(0)
; __device__ __forceinline__ unsigned pk2(float lo, float hi) { return pg8::cvt_pk_bf16(lo, hi); }
;     ...
;         for (int rb = 0; rb < 2; ++rb) {
;             float l = lrun[rb] + X[(rp * 68 + 66 + rb) * 64 + lane]; l += __shfl_xor(l, 16); l += __shfl_xor(l, 32);
;             const float inv = 1.0f / l;
;             bf16* orow = Op + (size_t)(32 * rp + 16 * rb + fr) * ldo + 4 * fq;
; #pragma unroll
;             for (int db = 0; db < 8; ++db) { float v[4];
; #pragma unroll
;                 for (int i = 0; i < 4; ++i) v[i] = (o[rb][db][i] + X[(rp * 68 + rb * 32 + db * 4 + i) * 64 + lane]) * inv;
;                 u32x2 ov; ov.x = pk2(v[0], v[1]); ov.y = pk2(v[2], v[3]); *(u32x2*)(orow + 16 * db) = ov; }
;         }
;     }
	v_add_f32_e32 v40, v66, v228
	v_mul_f32_e32 v43, v33, v40
	v_add_f32_e32 v40, v67, v229
	v_mul_f32_e32 v33, v33, v40
	v_cvt_pk_bf16_f32 v40, v39, v42
	v_cvt_pk_bf16_f32 v41, v43, v33
	ds_read_b32 v33, v38 offset:17152
	global_store_dwordx2 v[36:37], v[40:41], off offset:224
	s_waitcnt lgkmcnt(0)
	v_add_f32_e32 v33, v150, v33
	ds_bpermute_b32 v36, v162, v33
	s_waitcnt lgkmcnt(0)
	v_add_f32_e32 v33, v33, v36
	ds_bpermute_b32 v36, v163, v33
	s_waitcnt lgkmcnt(0)
	v_add_f32_e32 v33, v33, v36
	v_div_scale_f32 v36, s[58:59], v33, v33, 1.0
	v_rcp_f32_e32 v37, v36
	s_nop 0
	v_fma_f32 v39, -v36, v37, 1.0
	v_fmac_f32_e32 v37, v39, v37
	v_div_scale_f32 v39, vcc, 1.0, v33, 1.0
	v_mul_f32_e32 v40, v39, v37
	v_fma_f32 v41, -v36, v40, v39
	v_fmac_f32_e32 v40, v41, v37
	v_fma_f32 v36, -v36, v40, v39
	v_div_fmas_f32 v36, v36, v37, v40
	v_div_fixup_f32 v36, v36, v33, 1.0
	v_ashrrev_i32_e32 v33, 31, v32
	v_lshlrev_b64 v[32:33], 12, v[32:33]
	v_lshl_add_u64 v[32:33], v[34:35], 0, v[32:33]
	ds_read2st64_b32 v[228:229], v38 offset0:32 offset1:33
	ds_read2st64_b32 v[232:233], v38 offset0:34 offset1:35
	ds_read2st64_b32 v[240:241], v38 offset0:36 offset1:37
	ds_read2st64_b32 v[244:245], v38 offset0:38 offset1:39
	ds_read2st64_b32 v[248:249], v38 offset0:40 offset1:41
	s_waitcnt lgkmcnt(4)
	v_add_f32_e32 v28, v28, v228
	v_mul_f32_e32 v34, v28, v36
	v_add_f32_e32 v28, v29, v229
	ds_read2st64_b32 v[228:229], v38 offset0:42 offset1:43
	v_mul_f32_e32 v35, v36, v28
	s_waitcnt lgkmcnt(4)
	v_add_f32_e32 v28, v30, v232
	v_mul_f32_e32 v30, v36, v28
	v_add_f32_e32 v28, v31, v233
	ds_read2st64_b32 v[232:233], v38 offset0:44 offset1:45
	v_mul_f32_e32 v29, v36, v28
	v_cvt_pk_bf16_f32 v28, v34, v35
	v_cvt_pk_bf16_f32 v29, v30, v29
	global_store_dwordx2 v[32:33], v[28:29], off
	s_waitcnt lgkmcnt(4)
	v_add_f32_e32 v24, v24, v240
	v_mul_f32_e32 v28, v36, v24
	v_add_f32_e32 v24, v25, v241
	ds_read2st64_b32 v[240:241], v38 offset0:46 offset1:47
	v_mul_f32_e32 v29, v36, v24
	s_waitcnt lgkmcnt(4)
	v_add_f32_e32 v24, v26, v244
	v_mul_f32_e32 v26, v36, v24
	v_add_f32_e32 v24, v27, v245
	ds_read2st64_b32 v[244:245], v38 offset0:48 offset1:49
	v_mul_f32_e32 v25, v36, v24
	v_cvt_pk_bf16_f32 v24, v28, v29
	v_cvt_pk_bf16_f32 v25, v26, v25
	global_store_dwordx2 v[32:33], v[24:25], off offset:32
	s_waitcnt lgkmcnt(4)
	v_add_f32_e32 v20, v20, v248
	v_mul_f32_e32 v24, v36, v20
	v_add_f32_e32 v20, v21, v249
	ds_read2st64_b32 v[248:249], v38 offset0:50 offset1:51
	v_mul_f32_e32 v25, v36, v20
	s_waitcnt lgkmcnt(4)
	v_add_f32_e32 v20, v22, v228
	v_mul_f32_e32 v22, v36, v20
	v_add_f32_e32 v20, v23, v229
	ds_read2st64_b32 v[228:229], v38 offset0:52 offset1:53
	v_mul_f32_e32 v21, v36, v20
	v_cvt_pk_bf16_f32 v20, v24, v25
	v_cvt_pk_bf16_f32 v21, v22, v21
	global_store_dwordx2 v[32:33], v[20:21], off offset:64
	s_waitcnt lgkmcnt(4)
	v_add_f32_e32 v16, v16, v232
	v_mul_f32_e32 v20, v36, v16
	v_add_f32_e32 v16, v17, v233
	ds_read2st64_b32 v[232:233], v38 offset0:54 offset1:55
	v_mul_f32_e32 v21, v36, v16
	s_waitcnt lgkmcnt(4)
	v_add_f32_e32 v16, v18, v240
	v_mul_f32_e32 v18, v36, v16
	v_add_f32_e32 v16, v19, v241
	ds_read2st64_b32 v[240:241], v38 offset0:56 offset1:57
	v_mul_f32_e32 v17, v36, v16
	v_cvt_pk_bf16_f32 v16, v20, v21
	v_cvt_pk_bf16_f32 v17, v18, v17
	global_store_dwordx2 v[32:33], v[16:17], off offset:96
	s_waitcnt lgkmcnt(4)
	v_add_f32_e32 v12, v12, v244
	v_mul_f32_e32 v16, v36, v12
	v_add_f32_e32 v12, v13, v245
	ds_read2st64_b32 v[244:245], v38 offset0:58 offset1:59
	v_mul_f32_e32 v17, v36, v12
	s_waitcnt lgkmcnt(4)
	v_add_f32_e32 v12, v14, v248
	v_mul_f32_e32 v14, v36, v12
	v_add_f32_e32 v12, v15, v249
	ds_read2st64_b32 v[248:249], v38 offset0:60 offset1:61
	v_mul_f32_e32 v13, v36, v12
	v_cvt_pk_bf16_f32 v12, v16, v17
	v_cvt_pk_bf16_f32 v13, v14, v13
	global_store_dwordx2 v[32:33], v[12:13], off offset:128
	s_waitcnt lgkmcnt(4)
	v_add_f32_e32 v8, v8, v228
	v_mul_f32_e32 v12, v36, v8
	v_add_f32_e32 v8, v9, v229
	ds_read2st64_b32 v[228:229], v38 offset0:62 offset1:63
	v_mul_f32_e32 v13, v36, v8
	s_waitcnt lgkmcnt(4)
	v_add_f32_e32 v8, v10, v232
	v_mul_f32_e32 v10, v36, v8
	v_add_f32_e32 v8, v11, v233
	v_mul_f32_e32 v9, v36, v8
	v_cvt_pk_bf16_f32 v8, v12, v13
	v_cvt_pk_bf16_f32 v9, v10, v9
	global_store_dwordx2 v[32:33], v[8:9], off offset:160
	s_waitcnt lgkmcnt(3)
	v_add_f32_e32 v4, v4, v240
	v_mul_f32_e32 v8, v36, v4
	v_add_f32_e32 v4, v5, v241
	v_mul_f32_e32 v9, v36, v4
	s_waitcnt lgkmcnt(2)
	v_add_f32_e32 v4, v6, v244
	v_mul_f32_e32 v6, v36, v4
	v_add_f32_e32 v4, v7, v245
	v_mul_f32_e32 v5, v36, v4
	v_cvt_pk_bf16_f32 v4, v8, v9
	v_cvt_pk_bf16_f32 v5, v6, v5
	global_store_dwordx2 v[32:33], v[4:5], off offset:192
	s_waitcnt lgkmcnt(1)
	v_add_f32_e32 v0, v0, v248
	v_mul_f32_e32 v4, v36, v0
	v_add_f32_e32 v0, v1, v249
	v_mul_f32_e32 v5, v36, v0
	s_waitcnt lgkmcnt(0)
	v_add_f32_e32 v0, v2, v228
	v_mul_f32_e32 v2, v36, v0
	v_add_f32_e32 v0, v3, v229
	v_mul_f32_e32 v1, v36, v0
	v_cvt_pk_bf16_f32 v0, v4, v5
	v_cvt_pk_bf16_f32 v1, v2, v1
	global_store_dwordx2 v[32:33], v[0:1], off offset:224
	s_branch .LBB0_115

; #define LAS __attribute__((address_space(3)))
; __device__ __forceinline__ float bf2f(unsigned short h) { return __uint_as_float((unsigned)h << 16); }
; __device__ __forceinline__ unsigned pk2(float lo, float hi) { return pg8::cvt_pk_bf16(lo, hi); }
; __device__ __forceinline__ void gla_logdecay(float (&b)[16], float& blast, const LAS float* glrs, const float (&wcol)[16], const float bias, int d, int g, LAS float* tot) {
;     ...
;     float off = 0.f, all = 0.f;
; #pragma unroll
;     for (int gg = 0; gg < 4; ++gg) { const float tv = tot[gg * 128 + d]; all += tv; if (gg < g) off += tv; }
; #pragma unroll
;     for (int ii = 0; ii < 16; ++ii) b[ii] += off;
;     blast = all;
; __device__ __forceinline__ void gla_stepA(LAS unsigned char* lds, int item, const bf16* proj, const bf16* vtg, const float* glr, const float* W2, const float* b2, bf16* dST, float* decay) {
;     ...
;     { float kd[16];
; #pragma unroll
;       for (int ii = 0; ii < 16; ++ii) kd[ii] = bf2f(KR[(16 * g + ii) * QP + d]) * __expf(blast - b[ii]);
;       u32x4 p0, p1; p0.x = pk2(kd[0], kd[1]); p0.y = pk2(kd[2], kd[3]); p0.z = pk2(kd[4], kd[5]); p0.w = pk2(kd[6], kd[7]);
;       p1.x = pk2(kd[8], kd[9]); p1.y = pk2(kd[10], kd[11]); p1.z = pk2(kd[12], kd[13]); p1.w = pk2(kd[14], kd[15]);
;       *(LAS u32x4*)(KDT + d * VP + 16 * g) = p0; *(LAS u32x4*)(KDT + d * VP + 16 * g + 8) = p1; }
;     __syncthreads();
.LBB0_148:
	s_or_b64 exec, exec, s[36:37]
	v_cmp_lt_i32_e64 s[44:45], 0, v7
	v_cmp_lt_i32_e64 s[42:43], 1, v7
	v_cmp_lt_i32_e64 s[40:41], 2, v7
	v_cndmask_b32_e64 v1, 0, v2, s[44:45]
	v_add_f32_e32 v2, v3, v1
	v_cndmask_b32_e64 v1, v1, v2, s[42:43]
	v_add_f32_e32 v2, v4, v1
	v_cndmask_b32_e64 v1, v1, v2, s[40:41]
	v_cmp_lt_i32_e32 vcc, 3, v7
	v_add_f32_e32 v2, v5, v1
	s_movk_i32 s0, 0x1200
	v_cndmask_b32_e32 v1, v1, v2, vcc
	v_add_f32_e32 v3, v1, v9
	v_lshl_add_u32 v2, v6, 1, 0
	v_add_f32_e32 v20, v20, v1
	v_mad_u64_u32 v[4:5], s[14:15], v7, s0, v[2:3]
	ds_read_u16 v84, v4 offset:18432
	ds_read_u16 v88, v4 offset:18720
	ds_read_u16 v92, v4 offset:19008
	ds_read_u16 v96, v4 offset:19296
	ds_read_u16 v100, v4 offset:19584
	ds_read_u16 v104, v4 offset:19872
	ds_read_u16 v108, v4 offset:20160
	ds_read_u16 v112, v4 offset:20448
	ds_read_u16 v116, v4 offset:20736
	ds_read_u16 v120, v4 offset:21024
	ds_read_u16 v124, v4 offset:21312
	ds_read_u16 v128, v4 offset:21600
	v_sub_f32_e32 v20, v8, v20
	v_mul_f32_e32 v20, 0x3fb8aa3b, v20
	v_exp_f32_e32 v20, v20
	v_add_f32_e32 v22, v22, v1
	s_waitcnt lgkmcnt(11)
	v_lshlrev_b32_e32 v5, 16, v84
	ds_read_u16 v132, v4 offset:21888
	v_sub_f32_e32 v22, v8, v22
	v_mul_f32_e32 v5, v20, v5
	v_mul_f32_e32 v22, 0x3fb8aa3b, v22
	v_exp_f32_e32 v22, v22
	v_add_f32_e32 v23, v23, v1
	v_sub_f32_e32 v23, v8, v23
	s_waitcnt lgkmcnt(11)
	v_lshlrev_b32_e32 v20, 16, v88
	ds_read_u16 v136, v4 offset:22176
	v_mul_f32_e32 v20, v22, v20
	v_mul_f32_e32 v23, 0x3fb8aa3b, v23
	v_exp_f32_e32 v23, v23
	v_add_f32_e32 v21, v24, v1
	v_sub_f32_e32 v21, v8, v21
	s_waitcnt lgkmcnt(11)
	v_lshlrev_b32_e32 v22, 16, v92
	ds_read_u16 v140, v4 offset:22464
	v_mul_f32_e32 v22, v23, v22
	v_mul_f32_e32 v21, 0x3fb8aa3b, v21
	v_exp_f32_e32 v21, v21
	v_add_f32_e32 v19, v25, v1
	v_sub_f32_e32 v19, v8, v19
	s_waitcnt lgkmcnt(11)
	v_lshlrev_b32_e32 v23, 16, v96
	ds_read_u16 v84, v4 offset:22752
	v_mul_f32_e32 v21, v21, v23
	v_mul_f32_e32 v19, 0x3fb8aa3b, v19
	v_exp_f32_e32 v19, v19
	v_add_f32_e32 v18, v26, v1
	v_sub_f32_e32 v18, v8, v18
	s_waitcnt lgkmcnt(11)
	v_lshlrev_b32_e32 v23, 16, v100
	v_mul_f32_e32 v19, v19, v23
	v_mul_f32_e32 v18, 0x3fb8aa3b, v18
	v_exp_f32_e32 v18, v18
	v_add_f32_e32 v17, v27, v1
	v_sub_f32_e32 v17, v8, v17
	s_waitcnt lgkmcnt(10)
	v_lshlrev_b32_e32 v23, 16, v104
	v_mul_f32_e32 v18, v18, v23
	v_mul_f32_e32 v17, 0x3fb8aa3b, v17
	v_exp_f32_e32 v17, v17
	v_add_f32_e32 v16, v28, v1
	v_sub_f32_e32 v16, v8, v16
	s_waitcnt lgkmcnt(9)
	v_lshlrev_b32_e32 v23, 16, v108
	v_mul_f32_e32 v17, v17, v23
	v_mul_f32_e32 v16, 0x3fb8aa3b, v16
	v_exp_f32_e32 v16, v16
	v_add_f32_e32 v15, v29, v1
	v_sub_f32_e32 v15, v8, v15
	s_waitcnt lgkmcnt(8)
	v_lshlrev_b32_e32 v23, 16, v112
	v_mul_f32_e32 v16, v16, v23
	v_mul_f32_e32 v15, 0x3fb8aa3b, v15
	v_exp_f32_e32 v15, v15
	v_add_f32_e32 v14, v30, v1
	v_sub_f32_e32 v14, v8, v14
	s_waitcnt lgkmcnt(7)
	v_lshlrev_b32_e32 v23, 16, v116
	v_mul_f32_e32 v15, v15, v23
	v_mul_f32_e32 v14, 0x3fb8aa3b, v14
	v_exp_f32_e32 v14, v14
	v_add_f32_e32 v13, v31, v1
	v_sub_f32_e32 v13, v8, v13
	s_waitcnt lgkmcnt(6)
	v_lshlrev_b32_e32 v23, 16, v120
	v_mul_f32_e32 v14, v14, v23
	v_mul_f32_e32 v13, 0x3fb8aa3b, v13
	v_exp_f32_e32 v13, v13
	v_add_f32_e32 v12, v32, v1
	v_sub_f32_e32 v12, v8, v12
	s_waitcnt lgkmcnt(5)
	v_lshlrev_b32_e32 v23, 16, v124
	v_mul_f32_e32 v13, v13, v23
	v_mul_f32_e32 v12, 0x3fb8aa3b, v12
	v_exp_f32_e32 v12, v12
	v_add_f32_e32 v11, v33, v1
	v_sub_f32_e32 v11, v8, v11
	s_waitcnt lgkmcnt(4)
	v_lshlrev_b32_e32 v23, 16, v128
	v_mul_f32_e32 v23, v12, v23
	v_mul_f32_e32 v11, 0x3fb8aa3b, v11
	v_exp_f32_e32 v11, v11
	v_add_f32_e32 v10, v34, v1
	v_sub_f32_e32 v10, v8, v10
	s_waitcnt lgkmcnt(3)
	v_lshlrev_b32_e32 v12, 16, v132
	v_mul_f32_e32 v24, v11, v12
	v_mul_f32_e32 v10, 0x3fb8aa3b, v10
	v_exp_f32_e32 v10, v10
	v_add_f32_e32 v9, v35, v1
	v_sub_f32_e32 v3, v8, v3
	s_waitcnt lgkmcnt(2)
	v_lshlrev_b32_e32 v11, 16, v136
	v_mul_f32_e32 v25, v10, v11
	v_sub_f32_e32 v9, v8, v9
	v_mul_f32_e32 v3, 0x3fb8aa3b, v3
	v_mul_f32_e32 v9, 0x3fb8aa3b, v9
	v_exp_f32_e32 v3, v3
	v_exp_f32_e32 v9, v9
	s_waitcnt lgkmcnt(0)
	v_lshlrev_b32_e32 v4, 16, v84
	v_and_b32_e32 v1, 15, v0
	v_bfe_u32 v26, v0, 4, 2
	s_waitcnt lgkmcnt(1)
	v_lshlrev_b32_e32 v10, 16, v140
	v_mul_f32_e32 v3, v3, v4
	v_ashrrev_i32_e32 v0, 1, v0
	s_movk_i32 s0, 0xffe0
	v_mul_f32_e32 v27, v9, v10
	v_cvt_pk_bf16_f32 v8, v5, v20
	v_cvt_pk_bf16_f32 v9, v22, v21
	v_cvt_pk_bf16_f32 v10, v19, v18
	v_cvt_pk_bf16_f32 v11, v17, v16
	v_cvt_pk_bf16_f32 v12, v15, v14
	v_cvt_pk_bf16_f32 v13, v13, v23
	v_cvt_pk_bf16_f32 v14, v24, v25
	v_cvt_pk_bf16_f32 v15, v27, v3
	v_mul_u32_u24_e32 v3, 0x8e, v6
	v_lshlrev_b32_e32 v4, 5, v7
	v_and_or_b32 v24, v0, s0, v1
	v_lshl_add_u32 v0, v26, 4, 0
	s_movk_i32 s0, 0x90
	v_add3_u32 v2, v2, v3, v4
	v_mad_u64_u32 v[76:77], s[14:15], v24, s0, v[0:1]
	v_mad_u32_u24 v25, v1, s0, v0
	ds_write_b128 v2, v[8:11]
	ds_write_b128 v2, v[12:15] offset:16
	s_waitcnt lgkmcnt(0)
	s_barrier
; #define LAS __attribute__((address_space(3)))
; __device__ __forceinline__ unsigned pk2(float lo, float hi) { return pg8::cvt_pk_bf16(lo, hi); }
; #define MMA16(X, Y, ACC) ACC = __builtin_amdgcn_mfma_f32_16x16x32_bf16((X), (Y), (ACC), 0, 0, 0)
; __device__ __forceinline__ void gla_stepA(LAS unsigned char* lds, int item, const bf16* proj, const bf16* vtg, const float* glr, const float* W2, const float* b2, bf16* dST, float* decay) {
;     ...
;     f32x4 acc[2][8];
; #pragma unroll
;     for (int eb = 0; eb < 2; ++eb)
; #pragma unroll
;         for (int db = 0; db < 8; ++db) acc[eb][db] = (f32x4){0.f, 0.f, 0.f, 0.f};
; #pragma unroll
;     for (int ks = 0; ks < 2; ++ks) { bf16x8 vf[2];
; #pragma unroll
;         for (int eb = 0; eb < 2; ++eb) vf[eb] = *(const LAS bf16x8*)(VT + (32 * w + 16 * eb + fr) * VP + 32 * ks + 8 * fq);
; #pragma unroll
;         for (int db = 0; db < 8; ++db) { const bf16x8 kf = *(const LAS bf16x8*)(KDT + (16 * db + fr) * VP + 32 * ks + 8 * fq);
; #pragma unroll
;             for (int eb = 0; eb < 2; ++eb) MMA16(kf, vf[eb], acc[eb][db]); } }
;     bf16* dst = dST + (size_t)item * 32768;
; #pragma unroll
;     for (int eb = 0; eb < 2; ++eb)
; #pragma unroll
;         for (int db = 0; db < 8; ++db) { u32x2 ov; ov.x = pk2(acc[eb][db][0], acc[eb][db][1]); ov.y = pk2(acc[eb][db][2], acc[eb][db][3]);
;             *(u32x2*)(dst + (size_t)(32 * w + 16 * eb + fr) * 128 + 16 * db + 4 * fq) = ov; }
;     __syncthreads();
	ds_read_b128 v[84:87], v76 offset:36864
	ds_read_b128 v[88:91], v76 offset:39168
	ds_read_b128 v[92:95], v25
	ds_read_b128 v[96:99], v25 offset:2304
	ds_read_b128 v[100:103], v25 offset:4608
	ds_read_b128 v[104:107], v25 offset:6912
	ds_read_b128 v[108:111], v25 offset:9216
	ds_read_b128 v[112:115], v25 offset:11520
	ds_read_b128 v[116:119], v25 offset:13824
	ds_read_b128 v[120:123], v25 offset:16128
	ds_read_b128 v[124:127], v76 offset:36928
	ds_read_b128 v[128:131], v76 offset:39232
	s_waitcnt lgkmcnt(9)
	v_mfma_f32_16x16x32_bf16 v[16:19], v[92:95], v[84:87], 0
	s_add_u32 s14, s56, s10
	s_addc_u32 s15, s57, s11
	s_mov_b32 s0, 0x14d00000
	s_waitcnt lgkmcnt(10)
	v_mfma_f32_16x16x32_bf16 v[12:15], v[92:95], v[88:91], 0
	ds_read_b128 v[132:135], v25 offset:64
	s_add_i32 s46, s46, s52
	s_waitcnt lgkmcnt(9)
	v_mfma_f32_16x16x32_bf16 v[28:31], v[96:99], v[84:87], 0
	v_mfma_f32_16x16x32_bf16 v[20:23], v[96:99], v[88:91], 0
	ds_read_b128 v[136:139], v25 offset:4672
	s_waitcnt lgkmcnt(9)
	v_mfma_f32_16x16x32_bf16 v[36:39], v[100:103], v[84:87], 0
	v_mfma_f32_16x16x32_bf16 v[32:35], v[100:103], v[88:91], 0
	ds_read_b128 v[140:143], v25 offset:2368
	s_waitcnt lgkmcnt(9)
	v_mfma_f32_16x16x32_bf16 v[44:47], v[104:107], v[84:87], 0
	v_mfma_f32_16x16x32_bf16 v[40:43], v[104:107], v[88:91], 0
	ds_read_b128 v[92:95], v25 offset:6976
	s_waitcnt lgkmcnt(9)
	v_mfma_f32_16x16x32_bf16 v[52:55], v[108:111], v[84:87], 0
	v_mfma_f32_16x16x32_bf16 v[48:51], v[108:111], v[88:91], 0
	ds_read_b128 v[96:99], v25 offset:9280
	s_waitcnt lgkmcnt(9)
	v_mfma_f32_16x16x32_bf16 v[60:63], v[112:115], v[84:87], 0
	v_mfma_f32_16x16x32_bf16 v[56:59], v[112:115], v[88:91], 0
	ds_read_b128 v[100:103], v25 offset:11584
	s_waitcnt lgkmcnt(9)
	v_mfma_f32_16x16x32_bf16 v[68:71], v[116:119], v[84:87], 0
	v_mfma_f32_16x16x32_bf16 v[64:67], v[116:119], v[88:91], 0
	ds_read_b128 v[104:107], v25 offset:13888
	s_waitcnt lgkmcnt(9)
	v_mfma_f32_16x16x32_bf16 v[4:7], v[120:123], v[84:87], 0
	ds_read_b128 v[108:111], v25 offset:16192
	v_mfma_f32_16x16x32_bf16 v[8:11], v[120:123], v[88:91], 0
	s_waitcnt lgkmcnt(7)
	v_mfma_f32_16x16x32_bf16 v[80:83], v[132:135], v[124:127], v[16:19]
	s_nop 2
	s_waitcnt lgkmcnt(8)
	v_mfma_f32_16x16x32_bf16 v[0:3], v[132:135], v[128:131], v[12:15]
	s_nop 2
	s_waitcnt lgkmcnt(5)
	v_mfma_f32_16x16x32_bf16 v[28:31], v[140:143], v[124:127], v[28:31]
	v_mfma_f32_16x16x32_bf16 v[12:15], v[140:143], v[128:131], v[20:23]
	s_nop 2
	s_waitcnt lgkmcnt(6)
	v_mfma_f32_16x16x32_bf16 v[36:39], v[136:139], v[124:127], v[36:39]
	v_mfma_f32_16x16x32_bf16 v[16:19], v[136:139], v[128:131], v[32:35]
	s_waitcnt lgkmcnt(4)
	v_mfma_f32_16x16x32_bf16 v[32:35], v[92:95], v[124:127], v[44:47]
	v_mfma_f32_16x16x32_bf16 v[20:23], v[92:95], v[128:131], v[40:43]
	s_nop 2
	s_waitcnt lgkmcnt(3)
	v_mfma_f32_16x16x32_bf16 v[44:47], v[96:99], v[124:127], v[52:55]
	v_mfma_f32_16x16x32_bf16 v[40:43], v[96:99], v[128:131], v[48:51]
	s_nop 2
	s_waitcnt lgkmcnt(2)
	v_mfma_f32_16x16x32_bf16 v[52:55], v[100:103], v[124:127], v[60:63]
	v_mfma_f32_16x16x32_bf16 v[48:51], v[100:103], v[128:131], v[56:59]
	s_nop 2
	s_waitcnt lgkmcnt(1)
	v_mfma_f32_16x16x32_bf16 v[60:63], v[104:107], v[124:127], v[68:71]
	v_mfma_f32_16x16x32_bf16 v[56:59], v[104:107], v[128:131], v[64:67]
	s_nop 2
	v_ashrrev_i32_e32 v25, 31, v24
	s_waitcnt lgkmcnt(0)
	v_mfma_f32_16x16x32_bf16 v[4:7], v[108:111], v[124:127], v[4:7]
	v_mfma_f32_16x16x32_bf16 v[8:11], v[108:111], v[128:131], v[8:11]
	v_lshlrev_b64 v[64:65], 8, v[24:25]
	v_lshlrev_b32_e32 v25, 3, v26
	v_or_b32_e32 v64, v64, v25
	v_lshl_add_u64 v[26:27], s[14:15], 0, v[64:65]
	v_add_co_u32_e32 v26, vcc, s0, v26
	v_cvt_pk_bf16_f32 v64, v80, v81
	v_cvt_pk_bf16_f32 v65, v82, v83
	s_nop 1
	v_addc_co_u32_e32 v27, vcc, 0, v27, vcc
	global_store_dwordx2 v[26:27], v[64:65], off
	v_cvt_pk_bf16_f32 v28, v28, v29
	v_cvt_pk_bf16_f32 v29, v30, v31
	global_store_dwordx2 v[26:27], v[28:29], off offset:32
	v_cvt_pk_bf16_f32 v28, v36, v37
	v_cvt_pk_bf16_f32 v29, v38, v39
	global_store_dwordx2 v[26:27], v[28:29], off offset:64
	v_cvt_pk_bf16_f32 v28, v32, v33
	v_cvt_pk_bf16_f32 v29, v34, v35
	global_store_dwordx2 v[26:27], v[28:29], off offset:96
	v_cvt_pk_bf16_f32 v28, v44, v45
	v_cvt_pk_bf16_f32 v29, v46, v47
	global_store_dwordx2 v[26:27], v[28:29], off offset:128
	v_cvt_pk_bf16_f32 v28, v52, v53
	v_cvt_pk_bf16_f32 v29, v54, v55
	global_store_dwordx2 v[26:27], v[28:29], off offset:160
	v_cvt_pk_bf16_f32 v28, v60, v61
	v_cvt_pk_bf16_f32 v29, v62, v63
	global_store_dwordx2 v[26:27], v[28:29], off offset:192
	v_cvt_pk_bf16_f32 v4, v4, v5
	v_cvt_pk_bf16_f32 v5, v6, v7
	global_store_dwordx2 v[26:27], v[4:5], off offset:224
	v_or_b32_e32 v4, 16, v24
	v_ashrrev_i32_e32 v5, 31, v4
	v_lshlrev_b64 v[4:5], 8, v[4:5]
	v_or_b32_e32 v4, v4, v25
	v_lshl_add_u64 v[4:5], s[14:15], 0, v[4:5]
	v_cvt_pk_bf16_f32 v0, v0, v1
	v_cvt_pk_bf16_f32 v1, v2, v3
	v_add_co_u32_e32 v2, vcc, s0, v4
	v_readlane_b32 s0, v254, 57
	s_nop 0
	v_addc_co_u32_e32 v3, vcc, 0, v5, vcc
	global_store_dwordx2 v[2:3], v[0:1], off
	v_cvt_pk_bf16_f32 v0, v12, v13
	v_cvt_pk_bf16_f32 v1, v14, v15
	s_add_i32 s26, s26, s0
	v_readlane_b32 s14, v255, 3
	global_store_dwordx2 v[2:3], v[0:1], off offset:32
	v_cvt_pk_bf16_f32 v0, v16, v17
	v_cvt_pk_bf16_f32 v1, v18, v19
	v_readlane_b32 s15, v255, 4
	s_add_u32 s24, s24, s14
	global_store_dwordx2 v[2:3], v[0:1], off offset:64
	v_cvt_pk_bf16_f32 v0, v20, v21
	v_cvt_pk_bf16_f32 v1, v22, v23
	s_addc_u32 s25, s25, s15
	v_readlane_b32 s14, v255, 5
	global_store_dwordx2 v[2:3], v[0:1], off offset:96
	v_cvt_pk_bf16_f32 v0, v40, v41
	v_cvt_pk_bf16_f32 v1, v42, v43
	v_readlane_b32 s15, v255, 6
	s_add_u32 s10, s10, s14
	global_store_dwordx2 v[2:3], v[0:1], off offset:128
	v_cvt_pk_bf16_f32 v0, v48, v49
	v_cvt_pk_bf16_f32 v1, v50, v51
	s_addc_u32 s11, s11, s15
	global_store_dwordx2 v[2:3], v[0:1], off offset:160
	v_cvt_pk_bf16_f32 v0, v56, v57
	v_cvt_pk_bf16_f32 v1, v58, v59
	s_cmpk_gt_i32 s46, 0x1ff
	global_store_dwordx2 v[2:3], v[0:1], off offset:192
	v_cvt_pk_bf16_f32 v0, v8, v9
	v_cvt_pk_bf16_f32 v1, v10, v11
	global_store_dwordx2 v[2:3], v[0:1], off offset:224
	s_barrier
	s_cbranch_scc1 .LBB0_133
